# v12: v6 plus 64-bit accumulator zeroing also in the residual (down/out) GEMM tile loop
# speedup vs baseline: 1.0000x; 1.0000x over previous
; template <class Epi, class Sched, bool ALIGN_EPI = false, bool SP2 = false>
; __device__ __forceinline__ void gemm_phase(PG8_LAS unsigned char* lds, const Gemm g, const Sched& S, const Epi& E, const int wid) {
;     ...
; #pragma unroll
;         for (int a = 0; a < 2; ++a)
; #pragma unroll
;             for (int b = 0; b < 2; ++b)
; #pragma unroll
;                 for (int m = 0; m < 4; ++m)
; #pragma unroll
;                     for (int n = 0; n < 2; ++n) acc[a][b][m][n] = (f32x4){zf_, zf_, zf_, zf_};
;         cur = nxt; cA = nA; cB = nB; ++ui;
.LBB0_600:
	s_add_u32 s34, s34, 0x80
	s_addc_u32 s35, s35, 0
	s_add_u32 s47, s36, 0x100
	s_addc_u32 s52, s37, 0
	s_mov_b32 s36, 0
	v_mov_b64_e32 v[2:3], 0
	v_mov_b64_e32 v[4:5], 0
	v_mov_b64_e32 v[6:7], 0
	v_mov_b64_e32 v[8:9], 0
	v_mov_b64_e32 v[10:11], 0
	v_mov_b64_e32 v[12:13], 0
	v_mov_b64_e32 v[14:15], 0
	v_mov_b64_e32 v[16:17], 0
	v_mov_b64_e32 v[18:19], 0
	v_mov_b64_e32 v[20:21], 0
	v_mov_b64_e32 v[22:23], 0
	v_mov_b64_e32 v[24:25], 0
	v_mov_b64_e32 v[26:27], 0
	v_mov_b64_e32 v[28:29], 0
	v_mov_b64_e32 v[30:31], 0
	v_mov_b64_e32 v[32:33], 0
	v_mov_b64_e32 v[34:35], 0
	v_mov_b64_e32 v[36:37], 0
	v_mov_b64_e32 v[38:39], 0
	v_mov_b64_e32 v[40:41], 0
	v_mov_b64_e32 v[42:43], 0
	v_mov_b64_e32 v[44:45], 0
	v_mov_b64_e32 v[46:47], 0
	v_mov_b64_e32 v[48:49], 0
	v_mov_b64_e32 v[50:51], 0
	v_mov_b64_e32 v[52:53], 0
	v_mov_b64_e32 v[54:55], 0
	v_mov_b64_e32 v[56:57], 0
	v_mov_b64_e32 v[58:59], 0
	v_mov_b64_e32 v[60:61], 0
	v_mov_b64_e32 v[62:63], 0
	v_mov_b64_e32 v[64:65], 0
	v_mov_b64_e32 v[66:67], 0
	v_mov_b64_e32 v[68:69], 0
	v_mov_b64_e32 v[70:71], 0
	v_mov_b64_e32 v[72:73], 0
	v_mov_b64_e32 v[74:75], 0
	v_mov_b64_e32 v[76:77], 0
	v_mov_b64_e32 v[78:79], 0
	v_mov_b64_e32 v[80:81], 0
	v_mov_b64_e32 v[82:83], 0
	v_mov_b64_e32 v[84:85], 0
	v_mov_b64_e32 v[86:87], 0
	v_mov_b64_e32 v[88:89], 0
	v_mov_b64_e32 v[90:91], 0
	v_mov_b64_e32 v[92:93], 0
	v_mov_b64_e32 v[94:95], 0
	v_mov_b64_e32 v[96:97], 0
	v_mov_b64_e32 v[98:99], 0
	v_mov_b64_e32 v[100:101], 0
	v_mov_b64_e32 v[102:103], 0
	v_mov_b64_e32 v[104:105], 0
	v_mov_b64_e32 v[106:107], 0
	v_mov_b64_e32 v[108:109], 0
	v_mov_b64_e32 v[110:111], 0
	v_mov_b64_e32 v[112:113], 0
	v_mov_b64_e32 v[114:115], 0
	v_mov_b64_e32 v[116:117], 0
	v_mov_b64_e32 v[118:119], 0
	v_mov_b64_e32 v[120:121], 0
	v_mov_b64_e32 v[122:123], 0
	v_mov_b64_e32 v[124:125], 0
	v_mov_b64_e32 v[126:127], 0
	v_mov_b64_e32 v[128:129], 0
	s_waitcnt lgkmcnt(0)
